# LRU prompt-unit prologue: block-weight LDS writes wait at the end of the prologue so the weight, parameter and first-tile row loads are all in flight together
# speedup vs baseline: 1.0067x; 1.0066x over previous
.LBB0_249:
	s_mov_b64 s[4:5], s[26:27]
	s_or_b32 s19, s54, s49
	s_add_u32 s20, s4, 0xb100000
	s_mov_b64 s[58:59], s[26:27]
	s_mov_b32 s4, 25
	s_addc_u32 s21, s5, 0
	s_ashr_i32 s5, s4, 31
	s_lshl_b64 s[4:5], s[4:5], 3
	s_add_u32 s4, s0, s4
	s_addc_u32 s5, s1, s5
	s_load_dwordx2 s[22:23], s[4:5], 0x0
	s_mov_b32 s4, 26
	s_ashr_i32 s5, s4, 31
	s_lshl_b64 s[4:5], s[4:5], 3
	s_add_u32 s4, s0, s4
	s_addc_u32 s5, s1, s5
	s_load_dwordx2 s[28:29], s[4:5], 0x0
	s_mov_b32 s4, 28
	s_ashr_i32 s5, s4, 31
	s_lshl_b64 s[4:5], s[4:5], 3
	s_add_u32 s4, s0, s4
	s_addc_u32 s5, s1, s5
	s_load_dwordx2 s[16:17], s[4:5], 0x0
	s_mov_b32 s4, 30
	s_ashr_i32 s5, s4, 31
	s_lshl_b64 s[4:5], s[4:5], 3
	s_add_u32 s4, s0, s4
	s_addc_u32 s5, s1, s5
	s_load_dwordx2 s[38:39], s[4:5], 0x0
	s_mov_b32 s4, 31
	s_ashr_i32 s5, s4, 31
	s_lshl_b64 s[4:5], s[4:5], 3
	s_add_u32 s4, s0, s4
	s_addc_u32 s5, s1, s5
	s_load_dwordx2 s[40:41], s[4:5], 0x0
	s_mov_b32 s4, 7
	s_mov_b32 s4, 8
	s_mov_b64 s[12:13], s[30:31]
	s_mov_b64 s[14:15], s[30:31]
	s_mov_b64 s[34:35], s[26:27]
	s_mov_b64 s[4:5], s[26:27]
	v_mov_b32_e32 v92, v179
	s_lshl_b32 s61, s19, 13
	v_readfirstlane_b32 s18, v92
	s_ashr_i32 s57, s18, 8
	s_lshl_b32 s56, s57, 16
	s_lshl_b32 s60, s57, 1
	s_add_i32 s56, s56, 0
	s_add_i32 s60, s60, s42
	v_lshlrev_b32_e32 v1, 3, v92
	s_add_u32 s58, s58, s61
	v_and_b32_e32 v38, 56, v1
	s_addc_u32 s59, s59, 0
	v_lshlrev_b32_e32 v36, 1, v38
	v_mov_b32_e32 v37, v0
	v_lshl_add_u64 v[2:3], s[58:59], 0, v[36:37]
	s_ashr_i32 s61, s60, 31
	s_waitcnt vmcnt(4)
	v_lshl_add_u64 v[6:7], v[2:3], 0, s[96:97]
	v_bfe_u32 v93, v92, 3, 5
	s_lshl_b64 s[58:59], s[60:61], 17
	v_lshl_add_u64 v[8:9], v[6:7], 0, s[58:59]
	v_lshlrev_b32_e32 v10, 7, v93
	v_mov_b32_e32 v11, v0
	s_waitcnt lgkmcnt(0)
	s_barrier
	v_lshl_add_u64 v[2:3], v[8:9], 0, v[10:11]
	global_load_dwordx4 v[160:163], v[2:3], off
	v_mul_u32_u24_e32 v1, 0x48, v93
	v_add_lshl_u32 v1, v1, v38, 1
	v_or_b32_e32 v95, 32, v93
	v_add_u32_e32 v94, s56, v1
	s_waitcnt vmcnt(4)
	v_lshlrev_b32_e32 v12, 7, v95
	v_mov_b32_e32 v13, v0
	s_or_b32 s58, s60, 1
	s_ashr_i32 s59, s58, 31
	v_add_u32_e32 v1, 0x1200, v1
	s_lshl_b64 s[58:59], s[58:59], 17
	v_add_u32_e32 v96, s56, v1
	v_lshl_add_u64 v[6:7], v[6:7], 0, s[58:59]
	s_lshl_b32 s62, s19, 6
	s_lshl_b32 s19, s57, 10
	s_add_i32 s19, s19, s43
	v_and_b32_e32 v39, 15, v92
	s_add_i32 s19, s19, s62
	s_cmpk_lt_u32 s18, 0x100
	v_mov_b32_e32 v1, v0
	v_lshl_add_u64 v[148:149], v[8:9], 0, v[12:13]
	global_load_dwordx4 v[148:151], v[148:149], off
	v_lshl_add_u64 v[152:153], v[6:7], 0, v[10:11]
	global_load_dwordx4 v[152:155], v[152:153], off
	v_lshl_add_u64 v[156:157], v[6:7], 0, v[12:13]
	global_load_dwordx4 v[156:159], v[156:157], off
	v_or_b32_e32 v2, s19, v39
	v_ashrrev_i32_e32 v3, 31, v2
	v_lshlrev_b64 v[2:3], 2, v[2:3]
	s_waitcnt lgkmcnt(0)
	v_lshl_add_u64 v[4:5], s[16:17], 0, v[2:3]
	v_lshl_add_u64 v[6:7], s[38:39], 0, v[2:3]
	v_lshl_add_u64 v[2:3], s[40:41], 0, v[2:3]
	global_load_dword v97, v[4:5], off
	global_load_dword v98, v[6:7], off
	global_load_dword v43, v[2:3], off
	global_load_dword v99, v[4:5], off offset:64
	global_load_dword v100, v[6:7], off offset:64
	global_load_dword v42, v[2:3], off offset:64
	global_load_dword v101, v[4:5], off offset:128
	global_load_dword v102, v[6:7], off offset:128
	global_load_dword v40, v[2:3], off offset:128
	global_load_dword v103, v[4:5], off offset:192
	global_load_dword v104, v[6:7], off offset:192
	global_load_dword v41, v[2:3], off offset:192
	s_cselect_b64 s[16:17], -1, 0
	s_and_b64 s[38:39], s[16:17], exec
	s_cselect_b32 s19, -2, 0xbe
	v_mov_b32_e32 v2, v0
	v_mov_b32_e32 v3, v0
	v_add_u32_e32 v12, s19, v93
	v_mov_b64_e32 v[6:7], v[2:3]
	v_cmp_gt_u32_e32 vcc, s33, v12
	v_mov_b64_e32 v[4:5], v[0:1]
	s_and_saveexec_b64 s[38:39], vcc
	s_cbranch_execz .LBB0_251
	v_or_b32_e32 v4, s50, v12
	v_mov_b32_e32 v5, v0
	v_lshlrev_b64 v[4:5], 12, v[4:5]
	v_lshl_add_u64 v[4:5], s[20:21], 0, v[4:5]
	s_lshl_b32 s40, s62, 1
	s_mov_b32 s41, s63
	v_lshl_add_u64 v[4:5], v[4:5], 0, s[40:41]
	v_lshl_add_u64 v[4:5], v[4:5], 0, v[36:37]
	global_load_dwordx4 v[4:7], v[4:5], off offset:2048

.LBB0_255:
	s_or_b64 exec, exec, s[40:41]
	s_waitcnt vmcnt(14)
	v_mul_f32_e64 v1, |v43|, s87
	v_exp_f32_e32 v1, v1
	s_add_u32 s19, s34, 0x7100000
	s_addc_u32 s35, s35, 0
	s_add_u32 s39, s4, 0x9100000
	v_add_f32_e32 v1, 1.0, v1
	v_cmp_gt_f32_e32 vcc, s84, v1
	s_addc_u32 s57, s5, 0
	s_and_b64 s[40:41], s[16:17], exec
	v_cndmask_b32_e64 v2, 0, 32, vcc
	v_ldexp_f32 v1, v1, v2
	v_log_f32_e32 v1, v1
	v_max_f32_e64 v2, -v43, -v43
	v_cndmask_b32_e32 v43, 0, v232, vcc
	v_max_f32_e32 v2, 0, v2
	v_mul_f32_e32 v3, 0x3f317217, v1
	v_fma_f32 v3, v1, s80, -v3
	v_fmac_f32_e32 v3, 0x3377d1cf, v1
	v_fmac_f32_e32 v3, 0x3f317217, v1
	v_cmp_lt_f32_e64 s[4:5], |v1|, s81
	s_cselect_b32 s35, s35, s57
	s_cselect_b32 s19, s19, s39
	v_cndmask_b32_e64 v1, v1, v3, s[4:5]
	s_waitcnt vmcnt(11)
	v_mul_f32_e64 v3, |v42|, s87
	v_exp_f32_e32 v3, v3
	v_sub_f32_e32 v1, v1, v43
	v_add_f32_e32 v1, v2, v1
	v_mul_f32_e32 v105, 0xc1000000, v1
	v_add_f32_e32 v2, 1.0, v3
	v_cmp_gt_f32_e32 vcc, s84, v2
	v_max_f32_e64 v1, -v42, -v42
	v_max_f32_e32 v1, 0, v1
	v_cndmask_b32_e64 v3, 0, 32, vcc
	v_ldexp_f32 v2, v2, v3
	v_log_f32_e32 v2, v2
	v_cndmask_b32_e32 v42, 0, v232, vcc
	s_lshl_b64 s[40:41], s[6:7], 2
	s_add_u32 s28, s28, s40
	v_mul_f32_e32 v3, 0x3f317217, v2
	v_fma_f32 v3, v2, s80, -v3
	v_fmac_f32_e32 v3, 0x3377d1cf, v2
	v_fmac_f32_e32 v3, 0x3f317217, v2
	v_cmp_lt_f32_e64 s[4:5], |v2|, s81
	s_addc_u32 s29, s29, s41
	s_lshr_b32 s18, s18, 2
	v_cndmask_b32_e64 v2, v2, v3, s[4:5]
	s_waitcnt vmcnt(8)
	v_mul_f32_e64 v3, |v40|, s87
	v_exp_f32_e32 v3, v3
	v_sub_f32_e32 v2, v2, v42
	v_add_f32_e32 v1, v1, v2
	v_mul_f32_e32 v106, 0xc1000000, v1
	v_add_f32_e32 v2, 1.0, v3
	v_cmp_gt_f32_e32 vcc, s84, v2
	v_max_f32_e64 v1, -v40, -v40
	v_max_f32_e32 v1, 0, v1
	v_cndmask_b32_e64 v3, 0, 32, vcc
	v_ldexp_f32 v2, v2, v3
	v_log_f32_e32 v2, v2
	v_cndmask_b32_e32 v40, 0, v232, vcc
	v_bfe_u32 v44, v92, 4, 2
	s_and_b32 s18, s18, 48
	v_mul_f32_e32 v3, 0x3f317217, v2
	v_fma_f32 v3, v2, s80, -v3
	v_fmac_f32_e32 v3, 0x3377d1cf, v2
	v_fmac_f32_e32 v3, 0x3f317217, v2
	v_cmp_lt_f32_e64 s[4:5], |v2|, s81
	v_lshl_or_b32 v43, v44, 2, s18
	v_mad_u32_u24 v45, v43, s86, s86
	v_cndmask_b32_e64 v2, v2, v3, s[4:5]
	s_waitcnt vmcnt(5)
	v_mul_f32_e64 v3, |v41|, s87
	v_exp_f32_e32 v3, v3
	v_sub_f32_e32 v2, v2, v40
	v_add_f32_e32 v1, v1, v2
	v_mul_f32_e32 v107, 0xc1000000, v1
	v_add_f32_e32 v2, 1.0, v3
	v_cmp_gt_f32_e32 vcc, s84, v2
	v_max_f32_e64 v1, -v41, -v41
	v_max_f32_e32 v1, 0, v1
	v_cndmask_b32_e64 v3, 0, 32, vcc
	v_ldexp_f32 v2, v2, v3
	v_log_f32_e32 v2, v2
	v_and_b32_e32 v40, 7, v92
	v_mov_b32_e32 v41, v0
	v_add_u32_e32 v46, v45, v39
	v_mul_f32_e32 v3, 0x3f317217, v2
	v_fma_f32 v3, v2, s80, -v3
	v_fmac_f32_e32 v3, 0x3377d1cf, v2
	v_fmac_f32_e32 v3, 0x3f317217, v2
	v_cmp_lt_f32_e64 s[4:5], |v2|, s81
	v_or_b32_e32 v48, 3, v43
	v_lshlrev_b32_e32 v47, 1, v46
	v_cndmask_b32_e64 v2, v2, v3, s[4:5]
	v_cndmask_b32_e32 v3, 0, v232, vcc
	v_sub_f32_e32 v2, v2, v3
	v_add_f32_e32 v1, v1, v2
	v_mul_f32_e32 v108, 0xc1000000, v1
	v_or_b32_e32 v1, s18, v39
	s_add_u32 s18, s19, s38
	v_or_b32_e32 v2, s62, v38
	v_lshlrev_b32_e32 v38, 4, v44
	v_lshl_add_u32 v44, v40, 5, s56
	s_addc_u32 s19, s35, 0
	v_lshlrev_b32_e32 v40, 4, v40
	v_mov_b32_e32 v3, v0
	v_lshl_add_u64 v[78:79], s[18:19], 0, v[40:41]
	v_mad_u32_u24 v41, v43, s64, v39
	v_lshlrev_b64 v[2:3], 2, v[2:3]
	v_lshl_add_u32 v109, v41, 2, s56
	v_or_b32_e32 v41, 1, v43
	v_lshl_add_u64 v[76:77], s[28:29], 0, v[2:3]
	v_lshl_add_u64 v[2:3], s[22:23], 0, v[2:3]
	v_mad_i32_i24 v41, v41, -7, v46
	v_lshl_add_u64 v[80:81], v[2:3], 0, s[8:9]
	v_mul_u32_u24_e32 v3, 0x48, v43
	v_lshl_add_u32 v110, v41, 2, s56
	v_mad_u32_u24 v41, v43, s86, v234
	v_mad_u32_u24 v43, v43, s86, v235
	s_mov_b64 s[18:19], 0x1000
	v_add_u32_e32 v49, v43, v39
	v_lshl_add_u64 v[82:83], v[80:81], 0, s[18:19]
	s_mov_b64 s[18:19], 0x2000
	v_mad_i32_i24 v48, v48, -7, v49
	v_lshl_add_u64 v[84:85], v[80:81], 0, s[18:19]
	s_mov_b64 s[18:19], 0x3000
	v_lshl_add_u32 v112, v48, 2, s56
	v_or_b32_e32 v48, 16, v39
	v_lshl_add_u64 v[86:87], v[80:81], 0, s[18:19]
	v_mad_u32_u24 v2, v39, s85, v38
	v_or_b32_e32 v40, v3, v39
	v_or_b32_e32 v46, v41, v39
	v_or_b32_e32 v51, v3, v48
	v_or_b32_e32 v54, 32, v39
	v_or_b32_e32 v39, 48, v39
	s_add_u32 s18, s20, s38
	v_mul_u32_u24_e32 v1, 0x90, v1
	v_add_u32_e32 v42, s56, v38
	v_lshlrev_b32_e32 v40, 1, v40
	v_lshlrev_b32_e32 v46, 1, v46
	v_lshlrev_b32_e32 v50, 1, v49
	v_mad_u32_u24 v49, v48, s85, v38
	v_lshlrev_b32_e32 v51, 1, v51
	v_add_lshl_u32 v52, v45, v48, 1
	v_add_lshl_u32 v53, v41, v48, 1
	v_add_lshl_u32 v48, v43, v48, 1
	v_mad_u32_u24 v55, v54, s85, v38
	v_add_lshl_u32 v56, v3, v54, 1
	v_add_lshl_u32 v57, v45, v54, 1
	v_add_lshl_u32 v58, v41, v54, 1
	v_add_lshl_u32 v54, v43, v54, 1
	v_mad_u32_u24 v38, v39, s85, v38
	v_add_lshl_u32 v3, v3, v39, 1
	v_add_lshl_u32 v45, v45, v39, 1
	v_add_lshl_u32 v41, v41, v39, 1
	v_add_lshl_u32 v39, v43, v39, 1
	v_mul_u32_u24_e32 v43, 0x104, v93
	s_addc_u32 s19, s21, 0
	s_mov_b32 s34, 0
	v_cmp_lt_u32_sdwa s[4:5], v92, v233 src0_sel:BYTE_0 src1_sel:DWORD
	v_add_u32_e32 v111, 0x208, v109
	v_add_u32_e32 v113, 0x104, v109
	v_add_u32_e32 v114, 0x30c, v109
	v_or_b32_e32 v115, s50, v93
	v_or_b32_e32 v116, s50, v95
	v_lshl_add_u64 v[88:89], s[18:19], 0, v[36:37]
	v_add_u32_e32 v117, v42, v1
	v_add_u32_e32 v118, s56, v2
	v_add_u32_e32 v119, s56, v40
	v_add_u32_e32 v120, s56, v47
	v_add_u32_e32 v121, s56, v46
	v_add_u32_e32 v122, s56, v50
	v_add_u32_e32 v123, s56, v49
	v_add_u32_e32 v124, s56, v51
	v_add_u32_e32 v125, s56, v52
	v_add_u32_e32 v126, s56, v53
	v_add_u32_e32 v127, s56, v48
	v_add_u32_e32 v128, s56, v55
	v_add_u32_e32 v129, s56, v56
	v_add_u32_e32 v130, s56, v57
	v_add_u32_e32 v131, s56, v58
	v_add_u32_e32 v132, s56, v54
	v_add_u32_e32 v133, s56, v38
	v_add_u32_e32 v134, s56, v3
	v_add_u32_e32 v135, s56, v45
	v_add_u32_e32 v136, s56, v41
	v_add_u32_e32 v137, s56, v39
	v_add_u32_e32 v138, v44, v43
	s_waitcnt vmcnt(0)
	ds_write_b128 v94, v[160:163] offset:9216
	ds_write_b128 v96, v[148:151] offset:9216
	ds_write_b128 v94, v[152:155] offset:18432
	ds_write_b128 v96, v[156:159] offset:18432
